# speedup vs baseline: 1.0100x; 1.0100x over previous
; __device__ __forceinline__ float lo2f(unsigned u) { return __uint_as_float(u << 16); }
; __device__ __forceinline__ float hi2f(unsigned u) { return __uint_as_float(u & 0xffff0000u); }
; __device__ void phase_norm(const Params& p, int src_is_input, const bf16_t* delta, const float* gain, int final_out, int dry) {
;     ...
;   while (row < T_TOK) {
;     float dv[16], xv[16];
;     float ss = 0.f;
; #pragma unroll
;     for (int i = 0; i < 2; ++i) {
;       const unsigned du[4] = {dn[i].x, dn[i].y, dn[i].z, dn[i].w}, xu[4] = {xn[i].x, xn[i].y, xn[i].z, xn[i].w};
; #pragma unroll
;       for (int j = 0; j < 4; ++j) {
;         dv[i * 8 + 2 * j] = lo2f(du[j]); dv[i * 8 + 2 * j + 1] = hi2f(du[j]);
;         xv[i * 8 + 2 * j] = lo2f(xu[j]); xv[i * 8 + 2 * j + 1] = hi2f(xu[j]);
;       }
;     }
; #pragma unroll
;     for (int j = 0; j < 16; ++j) ss += dv[j] * dv[j];
;     const int nrow = row + stride;
;     if (nrow < T_TOK) NORM_FETCH(nrow);
.LBB0_1287:
	v_readlane_b32 s6, v254, 19
	v_readlane_b32 s7, v254, 20
	s_waitcnt vmcnt(5)
	v_add_u32_e32 v50, s6, v50
	s_mov_b32 s6, 0x10000
	v_cmp_gt_i32_e32 vcc, s6, v50
	v_cmp_lt_i32_e64 s[6:7], s65, v50
	s_waitcnt vmcnt(4)
	s_and_saveexec_b64 s[26:27], vcc
	s_cbranch_execz .LBB0_1289
	v_lshl_add_u64 v[18:19], v[56:57], 0, v[52:53]
	v_add_co_u32_e32 v30, vcc, 0x61a6000, v18
	v_lshl_add_u64 v[22:23], v[60:61], 0, v[52:53]
	s_nop 0
	v_addc_co_u32_e32 v31, vcc, 0, v19, vcc
	global_load_dwordx4 v[18:21], v[22:23], off
	s_nop 0
	global_load_dwordx4 v[22:25], v[22:23], off offset:1024
	s_nop 0
	global_load_dwordx4 v[26:29], v[30:31], off
	s_nop 0
	global_load_dwordx4 v[30:33], v[30:31], off offset:1024

; __device__ __forceinline__ int opaque_tid() { int t = threadIdx.x; asm volatile("" : "+v"(t)); return t; }
; __device__ void attn_item(const Params& p, int layer, int item, int dry) {
;   unsigned char* ws = p.ws;
;   const int tid = opaque_tid(), wid = tid >> 6, lane = tid & 63, r = lane & 15, quad = lane >> 4;
;   bf16_t* cat = (bf16_t*)(ws + O_S + S_CAT);
;   const bf16_t* kv = (const bf16_t*)(ws + O_KV) + layer * 512;
;   const int tile = item >> 2, h = item & 3;
;   const int tok0 = tile * 128;
;   const int seq = tok0 < 32768 ? (tok0 >> 11) : 16 + ((tok0 - 32768) >> 12);
;   bf16_t* Ks = (bf16_t*)smem;
;   bf16_t* Vt = (bf16_t*)(smem + 256 * 72 * 2);
;   const bf16_t* kvs = kv + (size_t)seq * 256 * 1024;
;   for (int i = 0; i < 4; ++i) {
;     int idx = tid + 512 * i;
;     int m = idx >> 3, d0 = (idx & 7) * 8;
;     uint4 uk = *(const uint4*)(kvs + (size_t)m * 1024 + h * 64 + d0);
;     *(uint4*)(Ks + m * 72 + d0) = uk;
;     uint4 uv = *(const uint4*)(kvs + (size_t)m * 1024 + 256 + h * 64 + d0);
;     unsigned uu[4] = {uv.x, uv.y, uv.z, uv.w};
;     for (int j = 0; j < 8; ++j) Vt[(d0 + j) * 264 + m] = (bf16_t)((j & 1) ? (uu[j >> 1] >> 16) : (uu[j >> 1] & 0xffff));
;   }
;   __syncthreads();
;   const int t = tok0 + wid * 16 + r;
;   bf16_t* qp = cat + (size_t)t * 1024 + 768 + h * 64;
;   bf16x8 qf[2];
;   qf[0] = *(const bf16x8*)(qp + quad * 8);
;   qf[1] = *(const bf16x8*)(qp + 32 + quad * 8);
.LBB0_1348:
	s_and_b64 vcc, exec, s[4:5]
	s_cbranch_vccz .LBB0_1365
	s_lshl_b32 s4, s27, 5
	s_and_b32 s6, s4, 0xffffff80
	s_addk_i32 s4, 0x8000
	s_lshr_b32 s4, s4, 12
	s_ashr_i32 s5, s27, 6
	s_add_i32 s4, s4, 16
	s_cmp_lt_i32 s6, 0x8000
	v_mov_b32_e32 v44, v208
	s_cselect_b32 s4, s5, s4
	s_ashr_i32 s5, s4, 31
	v_add_u32_e32 v10, 0x200, v44
	v_add_u32_e32 v18, 0x400, v44
	v_add_u32_e32 v26, 0x600, v44
	s_lshl_b64 s[4:5], s[4:5], 19
	v_ashrrev_i32_e32 v34, 3, v44
	v_ashrrev_i32_e32 v36, 3, v10
	v_ashrrev_i32_e32 v38, 3, v18
	v_ashrrev_i32_e32 v40, 3, v26
	s_add_u32 s4, s77, s4
	v_ashrrev_i32_e32 v35, 31, v34
	v_ashrrev_i32_e32 v37, 31, v36
	v_ashrrev_i32_e32 v39, 31, v38
	v_ashrrev_i32_e32 v41, 31, v40
	s_addc_u32 s5, s78, s5
	v_lshlrev_b32_e32 v0, 3, v44
	v_lshlrev_b64 v[2:3], 11, v[34:35]
	s_lshl_b32 s7, s27, 7
	v_lshlrev_b64 v[10:11], 11, v[36:37]
	v_lshlrev_b64 v[18:19], 11, v[38:39]
	v_lshlrev_b64 v[26:27], 11, v[40:41]
	v_and_b32_e32 v42, 56, v0
	v_lshl_add_u64 v[2:3], s[4:5], 0, v[2:3]
	s_and_b32 s66, s7, 0x180
	v_lshl_add_u64 v[10:11], s[4:5], 0, v[10:11]
	v_lshl_add_u64 v[18:19], s[4:5], 0, v[18:19]
	v_lshl_add_u64 v[26:27], s[4:5], 0, v[26:27]
	v_lshlrev_b32_e32 v0, 1, v42
	v_lshl_add_u64 v[2:3], v[2:3], 0, s[66:67]
	v_lshl_add_u64 v[10:11], v[10:11], 0, s[66:67]
	v_lshl_add_u64 v[18:19], v[18:19], 0, s[66:67]
	v_lshl_add_u64 v[26:27], v[26:27], 0, s[66:67]
	v_lshl_add_u64 v[6:7], v[2:3], 0, v[0:1]
	v_lshl_add_u64 v[14:15], v[10:11], 0, v[0:1]
	v_lshl_add_u64 v[22:23], v[18:19], 0, v[0:1]
	v_lshl_add_u64 v[30:31], v[26:27], 0, v[0:1]
	global_load_dwordx4 v[2:5], v[6:7], off
	s_nop 0
	global_load_dwordx4 v[6:9], v[6:7], off offset:512
	s_nop 0
	global_load_dwordx4 v[10:13], v[14:15], off
	s_nop 0
	global_load_dwordx4 v[14:17], v[14:15], off offset:512
	s_nop 0
	global_load_dwordx4 v[18:21], v[22:23], off
	s_nop 0
	global_load_dwordx4 v[22:25], v[22:23], off offset:512
	s_nop 0
	global_load_dwordx4 v[26:29], v[30:31], off
	s_nop 0
	global_load_dwordx4 v[30:33], v[30:31], off offset:512
	s_movk_i32 s7, 0x90
	v_mul_u32_u24_e32 v41, 0x251, v42
	v_mad_u64_u32 v[42:43], s[4:5], v34, s7, v[0:1]
	v_lshl_add_u32 v43, v34, 1, v41
	v_mad_u64_u32 v[34:35], s[4:5], v36, s7, v[0:1]
	v_lshl_add_u32 v35, v36, 1, v41
	v_mad_u64_u32 v[36:37], s[4:5], v38, s7, v[0:1]
	v_lshl_add_u32 v37, v38, 1, v41
	v_mad_u64_u32 v[38:39], s[4:5], v40, s7, v[0:1]
	v_lshl_add_u32 v0, v40, 1, v41
	v_and_b32_e32 v60, 15, v44
	v_bfe_u32 v61, v44, 4, 2
	s_mov_b64 s[4:5], 0xe1a6600
	s_waitcnt vmcnt(7)
	ds_write_b128 v42, v[2:5]
	s_waitcnt vmcnt(6)
	ds_write_b16 v43, v6 offset:36864
	ds_write_b16_d16_hi v43, v6 offset:37456
	ds_write_b16 v43, v7 offset:38048
	ds_write_b16_d16_hi v43, v7 offset:38640
	ds_write_b16 v43, v8 offset:39232
	ds_write_b16_d16_hi v43, v8 offset:39824
	ds_write_b16 v43, v9 offset:40416
	ds_write_b16_d16_hi v43, v9 offset:41008
	s_waitcnt vmcnt(5)
	ds_write_b128 v34, v[10:13]
	s_waitcnt vmcnt(4)
	ds_write_b16 v35, v14 offset:36864
	ds_write_b16_d16_hi v35, v14 offset:37456
	ds_write_b16 v35, v15 offset:38048
	ds_write_b16_d16_hi v35, v15 offset:38640
	ds_write_b16 v35, v16 offset:39232
	ds_write_b16_d16_hi v35, v16 offset:39824
	ds_write_b16 v35, v17 offset:40416
	ds_write_b16_d16_hi v35, v17 offset:41008
	s_waitcnt vmcnt(3)
	ds_write_b128 v36, v[18:21]
	s_waitcnt vmcnt(2)
	ds_write_b16 v37, v22 offset:36864
	ds_write_b16_d16_hi v37, v22 offset:37456
	ds_write_b16 v37, v23 offset:38048
	ds_write_b16_d16_hi v37, v23 offset:38640
	ds_write_b16 v37, v24 offset:39232
	ds_write_b16_d16_hi v37, v24 offset:39824
	ds_write_b16 v37, v25 offset:40416
	ds_write_b16_d16_hi v37, v25 offset:41008
	s_waitcnt vmcnt(1)
	ds_write_b128 v38, v[26:29]
	s_waitcnt vmcnt(0)
	ds_write_b16 v0, v30 offset:36864
	ds_write_b16_d16_hi v0, v30 offset:37456
	ds_write_b16 v0, v31 offset:38048
	ds_write_b16_d16_hi v0, v31 offset:38640
	ds_write_b16 v0, v32 offset:39232
	ds_write_b16_d16_hi v0, v32 offset:39824
	ds_write_b16 v0, v33 offset:40416
	ds_write_b16_d16_hi v0, v33 offset:41008
	v_ashrrev_i32_e32 v0, 2, v44
	v_and_b32_e32 v0, -16, v0
	v_add_u32_e32 v0, s6, v0
	v_or_b32_e32 v2, v0, v60
	v_ashrrev_i32_e32 v3, 31, v2
	v_lshlrev_b64 v[2:3], 11, v[2:3]
	v_lshl_add_u64 v[2:3], s[14:15], 0, v[2:3]
	v_lshl_add_u64 v[2:3], v[2:3], 0, s[66:67]
	v_lshl_add_u64 v[54:55], v[2:3], 0, s[4:5]
	v_lshlrev_b32_e32 v0, 4, v61
	v_lshl_add_u64 v[34:35], v[54:55], 0, v[0:1]
	global_load_dwordx4 v[2:5], v[34:35], off
	global_load_dwordx4 v[56:59], v[34:35], off offset:64
	s_waitcnt lgkmcnt(0)
	s_barrier
; __device__ void attn_item(const Params& p, int layer, int item, int dry) {
;     ...
;   f32x4 s[16];
;   for (int mt = 0; mt < 16; ++mt) {
;     s[mt] = f32x4{0.f, 0.f, 0.f, 0.f};
;     for (int ks = 0; ks < 2; ++ks) {
;       bf16x8 a = *(const bf16x8*)(Ks + (mt * 16 + r) * 72 + ks * 32 + quad * 8);
;       s[mt] = __builtin_amdgcn_mfma_f32_16x16x32_bf16(a, qf[ks], s[mt], 0, 0, 0);
;     }
;   }
;   float mx = -1e30f;
;   for (int mt = 0; mt < 16; ++mt)
;     for (int j = 0; j < 4; ++j) mx = fmaxf(mx, s[mt][j]);
;   mx = fmaxf(mx, __shfl_xor(mx, 16));
;   mx = fmaxf(mx, __shfl_xor(mx, 32));
	v_mad_u32_u24 v98, v60, s7, v0
	ds_read_b128 v[38:41], v98 offset:18432
	ds_read_b128 v[6:9], v98
	ds_read_b128 v[10:13], v98 offset:2304
	ds_read_b128 v[14:17], v98 offset:4608
	ds_read_b128 v[18:21], v98 offset:6912
	ds_read_b128 v[22:25], v98 offset:9216
	ds_read_b128 v[26:29], v98 offset:11520
	ds_read_b128 v[30:33], v98 offset:13824
	ds_read_b128 v[34:37], v98 offset:16128
	s_mov_b32 s4, 0xf149f2ca
	s_waitcnt vmcnt(1) lgkmcnt(8)
	v_mfma_f32_16x16x32_bf16 v[62:65], v[38:41], v[2:5], 0
	ds_read_b128 v[38:41], v98 offset:20736
	s_waitcnt lgkmcnt(0)
	v_mfma_f32_16x16x32_bf16 v[66:69], v[38:41], v[2:5], 0
	ds_read_b128 v[38:41], v98 offset:23040
	s_waitcnt lgkmcnt(0)
	v_mfma_f32_16x16x32_bf16 v[70:73], v[38:41], v[2:5], 0
	ds_read_b128 v[38:41], v98 offset:25344
	s_waitcnt lgkmcnt(0)
	v_mfma_f32_16x16x32_bf16 v[74:77], v[38:41], v[2:5], 0
	ds_read_b128 v[38:41], v98 offset:27648
	s_waitcnt lgkmcnt(0)
	v_mfma_f32_16x16x32_bf16 v[78:81], v[38:41], v[2:5], 0
	ds_read_b128 v[38:41], v98 offset:29952
	s_waitcnt lgkmcnt(0)
	v_mfma_f32_16x16x32_bf16 v[82:85], v[38:41], v[2:5], 0
	ds_read_b128 v[38:41], v98 offset:64
	v_mfma_f32_16x16x32_bf16 v[6:9], v[6:9], v[2:5], 0
	s_waitcnt vmcnt(0) lgkmcnt(0)
	v_mfma_f32_16x16x32_bf16 v[86:89], v[38:41], v[56:59], v[6:9]
	s_nop 5
	ds_read_b128 v[6:9], v98 offset:2368
	v_mfma_f32_16x16x32_bf16 v[10:13], v[10:13], v[2:5], 0
	s_waitcnt lgkmcnt(0)
	v_mfma_f32_16x16x32_bf16 v[90:93], v[6:9], v[56:59], v[10:13]
	ds_read_b128 v[6:9], v98 offset:4672
	v_mfma_f32_16x16x32_bf16 v[14:17], v[14:17], v[2:5], 0
	s_waitcnt lgkmcnt(0)
	v_mfma_f32_16x16x32_bf16 v[94:97], v[6:9], v[56:59], v[14:17]
	ds_read_b128 v[6:9], v98 offset:6976
	v_mfma_f32_16x16x32_bf16 v[18:21], v[18:21], v[2:5], 0
	s_waitcnt lgkmcnt(0)
	v_mfma_f32_16x16x32_bf16 v[50:53], v[6:9], v[56:59], v[18:21]
	ds_read_b128 v[6:9], v98 offset:9280
	v_mfma_f32_16x16x32_bf16 v[22:25], v[22:25], v[2:5], 0
	s_waitcnt lgkmcnt(0)
	v_mfma_f32_16x16x32_bf16 v[46:49], v[6:9], v[56:59], v[22:25]
	ds_read_b128 v[6:9], v98 offset:11584
	v_mfma_f32_16x16x32_bf16 v[26:29], v[26:29], v[2:5], 0
	s_waitcnt lgkmcnt(0)
	v_mfma_f32_16x16x32_bf16 v[42:45], v[6:9], v[56:59], v[26:29]
	ds_read_b128 v[6:9], v98 offset:13888
	v_mfma_f32_16x16x32_bf16 v[30:33], v[30:33], v[2:5], 0
	s_waitcnt lgkmcnt(0)
	v_mfma_f32_16x16x32_bf16 v[38:41], v[6:9], v[56:59], v[30:33]
	ds_read_b128 v[6:9], v98 offset:16192
	v_mfma_f32_16x16x32_bf16 v[34:37], v[34:37], v[2:5], 0
	s_waitcnt lgkmcnt(0)
	v_mfma_f32_16x16x32_bf16 v[34:37], v[6:9], v[56:59], v[34:37]
	ds_read_b128 v[6:9], v98 offset:18496
	s_waitcnt lgkmcnt(0)
	v_mfma_f32_16x16x32_bf16 v[30:33], v[6:9], v[56:59], v[62:65]
	ds_read_b128 v[6:9], v98 offset:20800
	s_nop 1
	ds_read_b128 v[62:65], v98 offset:32320
	s_waitcnt lgkmcnt(1)
	v_mfma_f32_16x16x32_bf16 v[26:29], v[6:9], v[56:59], v[66:69]
	ds_read_b128 v[6:9], v98 offset:23104
	s_waitcnt lgkmcnt(0)
	v_mfma_f32_16x16x32_bf16 v[22:25], v[6:9], v[56:59], v[70:73]
	ds_read_b128 v[6:9], v98 offset:25408
	s_waitcnt lgkmcnt(0)
	v_mfma_f32_16x16x32_bf16 v[18:21], v[6:9], v[56:59], v[74:77]
	ds_read_b128 v[6:9], v98 offset:27712
	s_waitcnt lgkmcnt(0)
	v_mfma_f32_16x16x32_bf16 v[14:17], v[6:9], v[56:59], v[78:81]
	ds_read_b128 v[6:9], v98 offset:30016
	s_waitcnt lgkmcnt(0)
	v_mfma_f32_16x16x32_bf16 v[10:13], v[6:9], v[56:59], v[82:85]
	ds_read_b128 v[6:9], v98 offset:32256
	s_waitcnt lgkmcnt(0)
	v_mfma_f32_16x16x32_bf16 v[6:9], v[6:9], v[2:5], 0
	v_mfma_f32_16x16x32_bf16 v[6:9], v[62:65], v[56:59], v[6:9]
	ds_read_b128 v[62:65], v98 offset:34560
	s_waitcnt lgkmcnt(0)
	v_mfma_f32_16x16x32_bf16 v[2:5], v[62:65], v[2:5], 0
	ds_read_b128 v[62:65], v98 offset:34624
	s_waitcnt lgkmcnt(0)
	v_mfma_f32_16x16x32_bf16 v[2:5], v[62:65], v[56:59], v[2:5]
	v_max3_f32 v56, v86, s4, v87
	v_max3_f32 v56, v56, v88, v89
	v_max3_f32 v56, v56, v90, v91
	v_max3_f32 v56, v56, v92, v93
	v_max3_f32 v56, v56, v94, v95
	v_max3_f32 v56, v56, v96, v97
	v_max3_f32 v56, v56, v50, v51
	v_max3_f32 v56, v56, v52, v53
	v_max3_f32 v56, v56, v46, v47
	v_max3_f32 v56, v56, v48, v49
	v_max3_f32 v56, v56, v42, v43
	v_max3_f32 v56, v56, v44, v45
	v_max3_f32 v56, v56, v38, v39
	v_max3_f32 v56, v56, v40, v41
	v_max3_f32 v56, v56, v34, v35
	v_max3_f32 v56, v56, v36, v37
	v_max3_f32 v56, v56, v30, v31
	v_max3_f32 v56, v56, v32, v33
	v_max3_f32 v56, v56, v26, v27
	v_max3_f32 v56, v56, v28, v29
	v_max3_f32 v56, v56, v22, v23
	v_max3_f32 v56, v56, v24, v25
	v_max3_f32 v56, v56, v18, v19
	v_max3_f32 v56, v56, v20, v21
	v_max3_f32 v56, v56, v14, v15
	v_max3_f32 v56, v56, v16, v17
	v_max3_f32 v56, v56, v10, v11
	v_max3_f32 v56, v56, v12, v13
	v_and_b32_e32 v58, 64, v228
	v_max3_f32 v56, v56, v6, v7
	v_xor_b32_e32 v57, 16, v228
	v_add_u32_e32 v59, 64, v58
	v_max3_f32 v56, v56, v8, v9
	v_cmp_lt_i32_e32 vcc, v57, v59
	v_max3_f32 v56, v56, v2, v3
	v_max3_f32 v56, v56, v4, v5
	v_cndmask_b32_e32 v57, v228, v57, vcc
	v_lshlrev_b32_e32 v58, 2, v57
	ds_bpermute_b32 v57, v58, v56
	s_movk_i32 s4, 0x210
	s_waitcnt lgkmcnt(0)
	v_max_f32_e32 v57, v57, v57
	v_max_f32_e32 v62, v56, v57
	v_xor_b32_e32 v56, 32, v228
	v_cmp_lt_i32_e32 vcc, v56, v59
	s_nop 1
	v_cndmask_b32_e32 v56, v228, v56, vcc
	v_lshlrev_b32_e32 v57, 2, v56
	ds_bpermute_b32 v59, v57, v62
	v_lshlrev_b32_e32 v56, 3, v61
	v_sub_u32_e32 v0, v0, v56
	s_andn2_b64 vcc, exec, s[24:25]
	s_waitcnt lgkmcnt(0)
; __device__ void attn_item(const Params& p, int layer, int item, int dry) {
;     ...
;   float sum = 0.f;
;   for (int mt = 0; mt < 16; ++mt)
;     for (int j = 0; j < 4; ++j) {
;       float e = __expf((s[mt][j] - mx) * 0.125f);
;       s[mt][j] = e;
;       sum += e;
;     }
;   sum += __shfl_xor(sum, 16);
;   sum += __shfl_xor(sum, 32);
;   const float inv = 1.f / sum;
	v_max_f32_e32 v59, v59, v59
	v_max_f32_e32 v59, v62, v59
	v_sub_f32_e32 v61, v86, v59
	v_mul_f32_e32 v61, 0x3e38aa3b, v61
	v_exp_f32_e32 v65, v61
	v_sub_f32_e32 v61, v87, v59
	v_mul_f32_e32 v61, 0x3e38aa3b, v61
	v_sub_f32_e32 v62, v90, v59
	v_mul_f32_e32 v62, 0x3e38aa3b, v62
	v_exp_f32_e32 v66, v61
	v_sub_f32_e32 v61, v88, v59
	v_mul_f32_e32 v61, 0x3e38aa3b, v61
	v_exp_f32_e32 v68, v62
	v_sub_f32_e32 v62, v91, v59
	v_mul_f32_e32 v62, 0x3e38aa3b, v62
	v_exp_f32_e32 v67, v61
	v_sub_f32_e32 v61, v89, v59
	v_mul_f32_e32 v61, 0x3e38aa3b, v61
	v_exp_f32_e32 v75, v62
	v_sub_f32_e32 v62, v92, v59
	v_mul_f32_e32 v62, 0x3e38aa3b, v62
	v_exp_f32_e32 v74, v61
	v_add_f32_e32 v61, 0, v65
	v_exp_f32_e32 v69, v62
	v_sub_f32_e32 v62, v93, v59
	v_add_f32_e32 v61, v66, v61
	v_mul_f32_e32 v62, 0x3e38aa3b, v62
	v_add_f32_e32 v61, v67, v61
	v_add_f32_e32 v61, v74, v61
	v_exp_f32_e32 v70, v62
	v_add_f32_e32 v61, v68, v61
	v_add_f32_e32 v61, v75, v61
	v_sub_f32_e32 v50, v50, v59
	v_add_f32_e32 v61, v69, v61
	v_mul_f32_e32 v50, 0x3e38aa3b, v50
	v_add_f32_e32 v71, v70, v61
	v_sub_f32_e32 v61, v94, v59
	v_mul_f32_e32 v61, 0x3e38aa3b, v61
	v_sub_f32_e32 v62, v95, v59
	v_exp_f32_e32 v90, v50
	v_sub_f32_e32 v50, v51, v59
	v_mul_f32_e32 v62, 0x3e38aa3b, v62
	v_sub_f32_e32 v63, v96, v59
	v_mul_f32_e32 v50, 0x3e38aa3b, v50
	v_exp_f32_e32 v61, v61
	v_mul_f32_e32 v63, 0x3e38aa3b, v63
	v_sub_f32_e32 v64, v97, v59
	v_exp_f32_e32 v62, v62
	v_mul_f32_e32 v64, 0x3e38aa3b, v64
	v_exp_f32_e32 v91, v50
	v_sub_f32_e32 v50, v52, v59
	v_exp_f32_e32 v63, v63
	v_mul_f32_e32 v50, 0x3e38aa3b, v50
	v_exp_f32_e32 v64, v64
	v_add_f32_e32 v71, v61, v71
	v_exp_f32_e32 v92, v50
	v_sub_f32_e32 v50, v53, v59
	v_add_f32_e32 v71, v62, v71
	v_mul_f32_e32 v50, 0x3e38aa3b, v50
	v_sub_f32_e32 v46, v46, v59
	v_add_f32_e32 v71, v63, v71
	v_mul_f32_e32 v46, 0x3e38aa3b, v46
	v_sub_f32_e32 v47, v47, v59
	v_add_f32_e32 v71, v64, v71
	v_exp_f32_e32 v53, v50
	v_mul_f32_e32 v47, 0x3e38aa3b, v47
	v_sub_f32_e32 v48, v48, v59
	v_add_f32_e32 v50, v90, v71
	v_exp_f32_e32 v46, v46
	v_mul_f32_e32 v48, 0x3e38aa3b, v48
	v_sub_f32_e32 v49, v49, v59
	v_add_f32_e32 v50, v91, v50
	v_exp_f32_e32 v47, v47
	v_mul_f32_e32 v49, 0x3e38aa3b, v49
	v_add_f32_e32 v50, v92, v50
	v_exp_f32_e32 v48, v48
	v_add_f32_e32 v50, v53, v50
	v_exp_f32_e32 v49, v49
	v_add_f32_e32 v50, v46, v50
	v_sub_f32_e32 v42, v42, v59
	v_add_f32_e32 v50, v47, v50
	v_mul_f32_e32 v42, 0x3e38aa3b, v42
	v_add_f32_e32 v50, v48, v50
	v_add_f32_e32 v71, v49, v50
	v_exp_f32_e32 v50, v42
	v_sub_f32_e32 v42, v43, v59
	v_mul_f32_e32 v42, 0x3e38aa3b, v42
	v_exp_f32_e32 v51, v42
	v_sub_f32_e32 v42, v44, v59
	v_mul_f32_e32 v42, 0x3e38aa3b, v42
	v_exp_f32_e32 v52, v42
	v_sub_f32_e32 v42, v45, v59
	v_mul_f32_e32 v42, 0x3e38aa3b, v42
	v_sub_f32_e32 v38, v38, v59
	v_mul_f32_e32 v38, 0x3e38aa3b, v38
	v_sub_f32_e32 v39, v39, v59
	v_exp_f32_e32 v45, v42
	v_mul_f32_e32 v39, 0x3e38aa3b, v39
	v_sub_f32_e32 v40, v40, v59
	v_add_f32_e32 v42, v50, v71
	v_exp_f32_e32 v38, v38
	v_mul_f32_e32 v40, 0x3e38aa3b, v40
	v_sub_f32_e32 v41, v41, v59
	v_add_f32_e32 v42, v51, v42
	v_exp_f32_e32 v39, v39
	v_mul_f32_e32 v41, 0x3e38aa3b, v41
	v_add_f32_e32 v42, v52, v42
	v_exp_f32_e32 v40, v40
	v_add_f32_e32 v42, v45, v42
	v_exp_f32_e32 v41, v41
	v_add_f32_e32 v42, v38, v42
	v_sub_f32_e32 v34, v34, v59
	v_add_f32_e32 v42, v39, v42
	v_mul_f32_e32 v34, 0x3e38aa3b, v34
	v_add_f32_e32 v42, v40, v42
	v_add_f32_e32 v71, v41, v42
	v_exp_f32_e32 v42, v34
	v_sub_f32_e32 v34, v35, v59
	v_mul_f32_e32 v34, 0x3e38aa3b, v34
	v_exp_f32_e32 v43, v34
	v_sub_f32_e32 v34, v36, v59
	v_mul_f32_e32 v34, 0x3e38aa3b, v34
	v_exp_f32_e32 v44, v34
	v_sub_f32_e32 v34, v37, v59
	v_mul_f32_e32 v34, 0x3e38aa3b, v34
	v_sub_f32_e32 v30, v30, v59
	v_mul_f32_e32 v30, 0x3e38aa3b, v30
	v_sub_f32_e32 v31, v31, v59
	v_exp_f32_e32 v37, v34
	v_mul_f32_e32 v31, 0x3e38aa3b, v31
	v_sub_f32_e32 v32, v32, v59
	v_add_f32_e32 v34, v42, v71
	v_exp_f32_e32 v30, v30
	v_mul_f32_e32 v32, 0x3e38aa3b, v32
	v_sub_f32_e32 v33, v33, v59
	v_add_f32_e32 v34, v43, v34
	v_exp_f32_e32 v31, v31
	v_mul_f32_e32 v33, 0x3e38aa3b, v33
	v_add_f32_e32 v34, v44, v34
	v_exp_f32_e32 v32, v32
	v_add_f32_e32 v34, v37, v34
	v_exp_f32_e32 v33, v33
	v_add_f32_e32 v34, v30, v34
	v_sub_f32_e32 v26, v26, v59
	v_add_f32_e32 v34, v31, v34
	v_mul_f32_e32 v26, 0x3e38aa3b, v26
	v_add_f32_e32 v34, v32, v34
	v_add_f32_e32 v71, v33, v34
	v_exp_f32_e32 v34, v26
	v_sub_f32_e32 v26, v27, v59
	v_mul_f32_e32 v26, 0x3e38aa3b, v26
	v_exp_f32_e32 v35, v26
	v_sub_f32_e32 v26, v28, v59
	v_mul_f32_e32 v26, 0x3e38aa3b, v26
	v_exp_f32_e32 v28, v26
	v_sub_f32_e32 v26, v29, v59
	v_mul_f32_e32 v26, 0x3e38aa3b, v26
	v_sub_f32_e32 v22, v22, v59
	v_mul_f32_e32 v22, 0x3e38aa3b, v22
	v_sub_f32_e32 v23, v23, v59
	v_exp_f32_e32 v36, v26
	v_mul_f32_e32 v23, 0x3e38aa3b, v23
	v_sub_f32_e32 v24, v24, v59
	v_add_f32_e32 v26, v34, v71
	v_exp_f32_e32 v22, v22
	v_mul_f32_e32 v24, 0x3e38aa3b, v24
	v_sub_f32_e32 v25, v25, v59
	v_add_f32_e32 v26, v35, v26
	v_exp_f32_e32 v23, v23
	v_mul_f32_e32 v25, 0x3e38aa3b, v25
	v_add_f32_e32 v26, v28, v26
	v_exp_f32_e32 v24, v24
	v_add_f32_e32 v26, v36, v26
	v_exp_f32_e32 v25, v25
	v_add_f32_e32 v26, v22, v26
	v_sub_f32_e32 v18, v18, v59
	v_sub_f32_e32 v20, v20, v59
	v_add_f32_e32 v26, v23, v26
	v_mul_f32_e32 v18, 0x3e38aa3b, v18
	v_sub_f32_e32 v19, v19, v59
	v_mul_f32_e32 v20, 0x3e38aa3b, v20
	v_add_f32_e32 v26, v24, v26
	v_mul_f32_e32 v19, 0x3e38aa3b, v19
	v_add_f32_e32 v29, v25, v26
	v_exp_f32_e32 v18, v18
	v_exp_f32_e32 v26, v20
	v_sub_f32_e32 v20, v21, v59
	v_exp_f32_e32 v19, v19
	v_mul_f32_e32 v20, 0x3e38aa3b, v20
	v_sub_f32_e32 v14, v14, v59
	v_mul_f32_e32 v14, 0x3e38aa3b, v14
; __device__ __forceinline__ unsigned short f2bf(float f) { return (unsigned short)(pack2(f, 0.f) & 0xffffu); }
; __device__ void attn_item(const Params& p, int layer, int item, int dry) {
;     ...
;   f32x4 o[4] = {};
;   for (int ks = 0; ks < 8; ++ks) {
;     bf16x8 pb;
;     for (int j = 0; j < 4; ++j) {
;       pb[j] = (short)f2bf(s[2 * ks][j]);
;       pb[4 + j] = (short)f2bf(s[2 * ks + 1][j]);
;     }
;     for (int dt = 0; dt < 4; ++dt) {
;       const bf16_t* vp = Vt + (dt * 16 + r) * 264 + ks * 32 + quad * 4;
;       uint2 v0 = *(const uint2*)vp, v1 = *(const uint2*)(vp + 16);
;       bf16x8 av;
;       av[0] = (short)(v0.x & 0xffff); av[1] = (short)(v0.x >> 16); av[2] = (short)(v0.y & 0xffff); av[3] = (short)(v0.y >> 16);
;       av[4] = (short)(v1.x & 0xffff); av[5] = (short)(v1.x >> 16); av[6] = (short)(v1.y & 0xffff); av[7] = (short)(v1.y >> 16);
;       o[dt] = __builtin_amdgcn_mfma_f32_16x16x32_bf16(av, pb, o[dt], 0, 0, 0);
	v_sub_f32_e32 v15, v15, v59
	v_exp_f32_e32 v27, v20
	v_mul_f32_e32 v15, 0x3e38aa3b, v15
	v_sub_f32_e32 v16, v16, v59
	v_add_f32_e32 v20, v18, v29
	v_exp_f32_e32 v14, v14
	v_mul_f32_e32 v16, 0x3e38aa3b, v16
	v_sub_f32_e32 v17, v17, v59
	v_add_f32_e32 v20, v19, v20
	v_exp_f32_e32 v15, v15
	v_mul_f32_e32 v17, 0x3e38aa3b, v17
	v_sub_f32_e32 v10, v10, v59
	v_add_f32_e32 v20, v26, v20
	v_exp_f32_e32 v16, v16
	v_mul_f32_e32 v10, 0x3e38aa3b, v10
	v_sub_f32_e32 v11, v11, v59
	v_add_f32_e32 v20, v27, v20
	v_exp_f32_e32 v17, v17
	v_mul_f32_e32 v11, 0x3e38aa3b, v11
	v_sub_f32_e32 v12, v12, v59
	v_add_f32_e32 v20, v14, v20
	v_exp_f32_e32 v10, v10
	v_mul_f32_e32 v12, 0x3e38aa3b, v12
	v_sub_f32_e32 v13, v13, v59
	v_add_f32_e32 v20, v15, v20
	v_exp_f32_e32 v11, v11
	v_mul_f32_e32 v13, 0x3e38aa3b, v13
	v_add_f32_e32 v20, v16, v20
	v_exp_f32_e32 v12, v12
	v_add_f32_e32 v20, v17, v20
	v_exp_f32_e32 v13, v13
	v_add_f32_e32 v20, v10, v20
	v_add_f32_e32 v20, v11, v20
	v_add_f32_e32 v20, v12, v20
	v_add_f32_e32 v86, v13, v20
	v_sub_f32_e32 v7, v7, v59
	v_mul_u32_u24_e32 v176, 0x250, v60
	v_lshrrev_b32_e32 v177, 3, v60
	v_add_u32_e32 v20, v176, v0
	v_lshl_add_u32 v20, v177, 3, v20
	v_mul_f32_e32 v29, 0x3e38aa3b, v7
	v_add_u32_e32 v21, 0x9000, v20
	v_add_u32_e32 v7, 0xb410, v20
	v_add_u32_e32 v0, 0xd820, v20
	v_add_u32_e32 v20, 0xfc30, v20
	v_cvt_pk_bf16_f32 v69, v69, v70
	ds_read2_b64 v[70:73], v21 offset1:4
	v_cvt_pk_bf16_f32 v68, v68, v75
	v_cvt_pk_bf16_f32 v67, v67, v74
	ds_read2_b64 v[74:77], v7 offset0:32 offset1:36
	ds_read2_b64 v[78:81], v0 offset0:64 offset1:68
	ds_read2_b64 v[82:85], v20 offset0:96 offset1:100
	v_sub_f32_e32 v6, v6, v59
	v_mul_f32_e32 v6, 0x3e38aa3b, v6
	v_exp_f32_e32 v6, v6
	s_waitcnt lgkmcnt(3)
	s_waitcnt lgkmcnt(2)
	s_waitcnt lgkmcnt(1)
	s_waitcnt lgkmcnt(0)
	v_exp_f32_e32 v29, v29
	v_cvt_pk_bf16_f32 v66, v65, v66
	v_add_f32_e32 v60, v6, v86
	ds_read2_b64 v[86:89], v21 offset0:8 offset1:12
	v_mfma_f32_16x16x32_bf16 v[70:73], v[70:73], v[66:69], 0
	v_add_f32_e32 v94, v29, v60
	v_sub_f32_e32 v8, v8, v59
	v_mul_f32_e32 v8, 0x3e38aa3b, v8
	v_mfma_f32_16x16x32_bf16 v[74:77], v[74:77], v[66:69], 0
	s_waitcnt lgkmcnt(0)
	v_sub_f32_e32 v2, v2, v59
	v_mfma_f32_16x16x32_bf16 v[78:81], v[78:81], v[66:69], 0
	v_mul_f32_e32 v2, 0x3e38aa3b, v2
	v_cvt_pk_bf16_f32 v27, v26, v27
	v_mfma_f32_16x16x32_bf16 v[66:69], v[82:85], v[66:69], 0
	v_cvt_pk_bf16_f32 v83, v63, v64
	v_cvt_pk_bf16_f32 v82, v61, v62
	ds_read2_b64 v[60:63], v0 offset0:72 offset1:76
	v_cvt_pk_bf16_f32 v85, v92, v53
	v_cvt_pk_bf16_f32 v84, v90, v91
	ds_read2_b64 v[90:93], v7 offset0:40 offset1:44
	v_cvt_pk_bf16_f32 v53, v52, v45
	s_waitcnt lgkmcnt(1)
	v_mfma_f32_16x16x32_bf16 v[70:73], v[86:89], v[82:85], v[70:73]
	ds_read2_b64 v[86:89], v20 offset0:104 offset1:108
	v_cvt_pk_bf16_f32 v52, v50, v51
	v_cvt_pk_bf16_f32 v51, v48, v49
	v_mfma_f32_16x16x32_bf16 v[60:63], v[60:63], v[82:85], v[78:81]
	v_cvt_pk_bf16_f32 v50, v46, v47
	ds_read2_b64 v[46:49], v0 offset0:80 offset1:84
	s_waitcnt lgkmcnt(2)
	ds_read2_b64 v[78:81], v21 offset0:16 offset1:20
	s_waitcnt lgkmcnt(2)
	v_mfma_f32_16x16x32_bf16 v[74:77], v[90:93], v[82:85], v[74:77]
	s_waitcnt lgkmcnt(0)
	v_cvt_pk_bf16_f32 v45, v44, v37
	v_mfma_f32_16x16x32_bf16 v[64:67], v[86:89], v[82:85], v[66:69]
	ds_read2_b64 v[82:85], v7 offset0:48 offset1:52
	v_cvt_pk_bf16_f32 v44, v42, v43
	v_cvt_pk_bf16_f32 v43, v40, v41
	v_mfma_f32_16x16x32_bf16 v[68:71], v[78:81], v[50:53], v[70:73]
	ds_read2_b64 v[78:81], v20 offset0:112 offset1:116
	v_cvt_pk_bf16_f32 v42, v38, v39
	ds_read2_b64 v[38:41], v0 offset0:88 offset1:92
	v_mfma_f32_16x16x32_bf16 v[46:49], v[46:49], v[50:53], v[60:63]
	s_waitcnt lgkmcnt(2)
	s_waitcnt lgkmcnt(1)
	v_cvt_pk_bf16_f32 v37, v28, v36
	ds_read2_b64 v[60:63], v21 offset0:24 offset1:28
	s_waitcnt lgkmcnt(1)
	v_mfma_f32_16x16x32_bf16 v[72:75], v[82:85], v[50:53], v[74:77]
	v_cvt_pk_bf16_f32 v36, v34, v35
	v_cvt_pk_bf16_f32 v35, v32, v33
	s_waitcnt lgkmcnt(0)
	v_mfma_f32_16x16x32_bf16 v[50:53], v[78:81], v[50:53], v[64:67]
	v_cvt_pk_bf16_f32 v34, v30, v31
	ds_read2_b64 v[30:33], v0 offset0:96 offset1:100
	v_exp_f32_e32 v90, v8
	ds_read2_b64 v[64:67], v7 offset0:56 offset1:60
	v_mfma_f32_16x16x32_bf16 v[60:63], v[60:63], v[42:45], v[68:71]
	v_sub_f32_e32 v8, v9, v59
	s_waitcnt lgkmcnt(1)
	v_mul_f32_e32 v8, 0x3e38aa3b, v8
	ds_read2_b64 v[68:71], v20 offset0:120 offset1:124
	v_mfma_f32_16x16x32_bf16 v[38:41], v[38:41], v[42:45], v[46:49]
	s_waitcnt lgkmcnt(1)
	v_exp_f32_e32 v9, v2
	ds_read2_b64 v[46:49], v21 offset0:32 offset1:36
	s_waitcnt lgkmcnt(1)
; __device__ __forceinline__ unsigned short f2bf(float f) { return (unsigned short)(pack2(f, 0.f) & 0xffffu); }
; __device__ void attn_item(const Params& p, int layer, int item, int dry) {
;     ...
;   for (int ks = 0; ks < 8; ++ks) {
;     bf16x8 pb;
;     for (int j = 0; j < 4; ++j) {
;       pb[j] = (short)f2bf(s[2 * ks][j]);
;       pb[4 + j] = (short)f2bf(s[2 * ks + 1][j]);
;     }
;     for (int dt = 0; dt < 4; ++dt) {
;       const bf16_t* vp = Vt + (dt * 16 + r) * 264 + ks * 32 + quad * 4;
;       uint2 v0 = *(const uint2*)vp, v1 = *(const uint2*)(vp + 16);
;       bf16x8 av;
;       av[0] = (short)(v0.x & 0xffff); av[1] = (short)(v0.x >> 16); av[2] = (short)(v0.y & 0xffff); av[3] = (short)(v0.y >> 16);
;       av[4] = (short)(v1.x & 0xffff); av[5] = (short)(v1.x >> 16); av[6] = (short)(v1.y & 0xffff); av[7] = (short)(v1.y >> 16);
;       o[dt] = __builtin_amdgcn_mfma_f32_16x16x32_bf16(av, pb, o[dt], 0, 0, 0);
;     }
;   }
;   for (int dt = 0; dt < 4; ++dt) {
;     uint2 ov;
;     ov.x = pack2(o[dt][0] * inv, o[dt][1] * inv);
;     ov.y = pack2(o[dt][2] * inv, o[dt][3] * inv);
;     if (!dry) *(uint2*)(qp + dt * 16 + quad * 4) = ov;
;   }
;   __syncthreads();
	v_mfma_f32_16x16x32_bf16 v[64:67], v[64:67], v[42:45], v[72:75]
	v_sub_f32_e32 v2, v3, v59
	v_exp_f32_e32 v76, v8
	s_waitcnt lgkmcnt(0)
	v_mfma_f32_16x16x32_bf16 v[42:45], v[68:71], v[42:45], v[50:53]
	v_mul_f32_e32 v2, 0x3e38aa3b, v2
	v_exp_f32_e32 v28, v2
	ds_read2_b64 v[50:53], v7 offset0:64 offset1:68
	v_mfma_f32_16x16x32_bf16 v[46:49], v[46:49], v[34:37], v[60:63]
	v_add_f32_e32 v8, v90, v94
	v_add_f32_e32 v8, v76, v8
	v_add_f32_e32 v2, v9, v8
	ds_read2_b64 v[60:63], v20 offset0:128 offset1:132
	v_mfma_f32_16x16x32_bf16 v[30:33], v[30:33], v[34:37], v[38:41]
	s_waitcnt lgkmcnt(1)
	v_add_f32_e32 v8, v28, v2
	v_sub_f32_e32 v2, v4, v59
	ds_read2_b64 v[38:41], v21 offset0:40 offset1:44
	s_waitcnt lgkmcnt(1)
	v_mfma_f32_16x16x32_bf16 v[50:53], v[50:53], v[34:37], v[64:67]
	v_mul_f32_e32 v2, 0x3e38aa3b, v2
	s_waitcnt lgkmcnt(0)
	v_mfma_f32_16x16x32_bf16 v[34:37], v[60:63], v[34:37], v[42:45]
	ds_read2_b64 v[60:63], v0 offset0:104 offset1:108
	v_cvt_pk_bf16_f32 v26, v18, v19
	v_cvt_pk_bf16_f32 v25, v24, v25
	v_cvt_pk_bf16_f32 v24, v22, v23
	v_exp_f32_e32 v18, v2
	v_sub_f32_e32 v19, v5, v59
	ds_read2_b64 v[2:5], v21 offset0:48 offset1:52
	ds_read2_b64 v[42:45], v7 offset0:72 offset1:76
	v_mfma_f32_16x16x32_bf16 v[38:41], v[38:41], v[24:27], v[46:49]
	v_cvt_pk_bf16_f32 v13, v12, v13
	v_cvt_pk_bf16_f32 v12, v10, v11
	v_cvt_pk_bf16_f32 v11, v16, v17
	ds_read2_b64 v[46:49], v20 offset0:136 offset1:140
	v_cvt_pk_bf16_f32 v10, v14, v15
	ds_read2_b64 v[14:17], v0 offset0:112 offset1:116
	s_waitcnt lgkmcnt(4)
	s_waitcnt lgkmcnt(3)
	s_waitcnt lgkmcnt(2)
	s_waitcnt lgkmcnt(1)
	s_waitcnt lgkmcnt(0)
	v_mfma_f32_16x16x32_bf16 v[30:33], v[60:63], v[24:27], v[30:33]
	v_mul_f32_e32 v19, 0x3e38aa3b, v19
	v_exp_f32_e32 v19, v19
	v_mfma_f32_16x16x32_bf16 v[2:5], v[2:5], v[10:13], v[38:41]
	v_add_f32_e32 v8, v18, v8
	s_nop 1
	ds_read2_b64 v[38:41], v20 offset0:144 offset1:148
	v_mfma_f32_16x16x32_bf16 v[42:45], v[42:45], v[24:27], v[50:53]
	s_waitcnt lgkmcnt(0)
	v_mfma_f32_16x16x32_bf16 v[22:25], v[46:49], v[24:27], v[34:37]
	s_nop 2
	ds_read2_b64 v[34:37], v7 offset0:80 offset1:84
	v_mfma_f32_16x16x32_bf16 v[14:17], v[14:17], v[10:13], v[30:33]
	s_waitcnt lgkmcnt(0)
	s_nop 0
	ds_read2_b64 v[30:33], v21 offset0:56 offset1:60
	v_mfma_f32_16x16x32_bf16 v[22:25], v[38:41], v[10:13], v[22:25]
	v_cvt_pk_bf16_f32 v41, v18, v19
	v_cvt_pk_bf16_f32 v40, v9, v28
	v_cvt_pk_bf16_f32 v39, v90, v76
	s_waitcnt lgkmcnt(0)
	v_cvt_pk_bf16_f32 v38, v6, v29
	v_mfma_f32_16x16x32_bf16 v[34:37], v[34:37], v[10:13], v[42:45]
	v_add_f32_e32 v21, v19, v8
	ds_read2_b64 v[8:11], v7 offset0:88 offset1:92
	ds_read2_b64 v[26:29], v0 offset0:120 offset1:124
	v_mfma_f32_16x16x32_bf16 v[2:5], v[30:33], v[38:41], v[2:5]
	ds_read2_b64 v[30:33], v20 offset0:152 offset1:156
	ds_bpermute_b32 v0, v58, v21
	s_waitcnt lgkmcnt(3)
	s_waitcnt lgkmcnt(2)
	s_waitcnt lgkmcnt(1)
	s_waitcnt lgkmcnt(0)
	v_add_f32_e32 v0, v21, v0
	ds_bpermute_b32 v18, v57, v0
	v_mfma_f32_16x16x32_bf16 v[6:9], v[8:11], v[38:41], v[34:37]
	v_mfma_f32_16x16x32_bf16 v[10:13], v[26:29], v[38:41], v[14:17]
	v_mfma_f32_16x16x32_bf16 v[14:17], v[30:33], v[38:41], v[22:25]
	s_cbranch_vccnz .LBB0_1351
	s_waitcnt lgkmcnt(0)
	v_add_f32_e32 v0, v0, v18
	v_div_scale_f32 v18, s[4:5], v0, v0, 1.0
	v_rcp_f32_e32 v19, v18
	v_mov_b32_e32 v57, v1
	v_lshl_add_u64 v[20:21], v[54:55], 0, v[56:57]
	v_fma_f32 v22, -v18, v19, 1.0
	v_fmac_f32_e32 v19, v22, v19
	v_div_scale_f32 v22, vcc, 1.0, v0, 1.0
	v_mul_f32_e32 v23, v22, v19
	v_fma_f32 v24, -v18, v23, v22
	v_fmac_f32_e32 v23, v24, v19
	v_fma_f32 v18, -v18, v23, v22
	v_div_fmas_f32 v18, v18, v19, v23
	v_div_fixup_f32 v0, v18, v0, 1.0
	v_pk_mul_f32 v[4:5], v[0:1], v[4:5] op_sel_hi:[0,1]
	v_pk_mul_f32 v[2:3], v[0:1], v[2:3] op_sel_hi:[0,1]
	v_cvt_pk_bf16_f32 v5, v4, v5
	v_cvt_pk_bf16_f32 v4, v2, v3
	global_store_dwordx2 v[20:21], v[4:5], off
	v_pk_mul_f32 v[2:3], v[0:1], v[8:9] op_sel_hi:[0,1]
	v_pk_mul_f32 v[4:5], v[0:1], v[6:7] op_sel_hi:[0,1]
	v_cvt_pk_bf16_f32 v3, v2, v3
	v_cvt_pk_bf16_f32 v2, v4, v5
	global_store_dwordx2 v[20:21], v[2:3], off offset:32
	v_pk_mul_f32 v[2:3], v[0:1], v[12:13] op_sel_hi:[0,1]
	v_pk_mul_f32 v[4:5], v[0:1], v[10:11] op_sel_hi:[0,1]
	v_cvt_pk_bf16_f32 v3, v2, v3
	v_cvt_pk_bf16_f32 v2, v4, v5
	global_store_dwordx2 v[20:21], v[2:3], off offset:64
	v_pk_mul_f32 v[2:3], v[0:1], v[16:17] op_sel_hi:[0,1]
	v_pk_mul_f32 v[4:5], v[0:1], v[14:15] op_sel_hi:[0,1]
	v_cvt_pk_bf16_f32 v3, v2, v3
	v_cvt_pk_bf16_f32 v2, v4, v5
	global_store_dwordx2 v[20:21], v[2:3], off offset:96
